# GEMM k-loop: static s_setprio 1 for waves 4-7 for the duration of the k-loop (reset before the epilogue)
# speedup vs baseline: 1.0032x; 1.0024x over previous
.LBB0_637:
	s_and_b64 s[2:3], s[8:9], exec
	v_readlane_b32 s2, v255, 26
	v_readlane_b32 s4, v255, 30
	v_readlane_b32 s3, v255, 27
	v_readlane_b32 s5, v255, 31
	s_cselect_b32 s24, s5, s3
	s_cselect_b32 s28, s4, s2
	v_readlane_b32 s2, v255, 24
	v_readlane_b32 s4, v255, 32
	v_readlane_b32 s3, v255, 25
	v_readlane_b32 s5, v255, 33
	s_cselect_b32 s29, s5, s3
	s_cselect_b32 s34, s4, s2
	v_readlane_b32 s2, v255, 23
	v_readlane_b32 s3, v255, 43
	s_cselect_b32 s14, s3, s2
	v_readlane_b32 s2, v255, 39
	s_cselect_b32 s39, s2, 0
	v_readlane_b32 s2, v255, 18
	v_readlane_b32 s3, v255, 40
	s_cselect_b32 s44, s3, s2
	s_lshl_b32 s45, s15, 8
	s_mul_i32 s2, s15, 0xfe
	s_add_i32 s45, s45, s39
	s_lshl_b32 s6, s47, 8
	s_add_i32 s4, s2, -1
	s_cmp_eq_u32 s44, 7
	s_cselect_b64 vcc, -1, 0
	s_and_b64 s[2:3], vcc, exec
	s_cselect_b32 s2, 0, s45
	s_cselect_b32 s40, s4, 0
	s_ashr_i32 s3, s2, 31
	v_mov_b32_e32 v175, v163
	s_mul_i32 s3, s3, s14
	s_mul_hi_u32 s4, s2, s14
	s_ashr_i32 s7, s6, 31
	s_add_i32 s3, s4, s3
	s_waitcnt vmcnt(1)
	v_ashrrev_i32_e32 v10, 6, v175
	s_waitcnt vmcnt(0)
	v_bfe_u32 v14, v175, 3, 3
	s_mul_i32 s2, s2, s14
	s_mul_i32 s4, s7, s14
	s_mul_hi_u32 s5, s6, s14
	v_lshl_or_b32 v6, v10, 5, v14
	s_add_i32 s5, s5, s4
	v_and_b32_e32 v0, 63, v175
	s_lshl_b64 s[2:3], s[2:3], 1
	s_mul_i32 s4, s6, s14
	s_add_u32 s2, s28, s2
	v_lshlrev_b32_e32 v176, 4, v0
	v_add_u32_e32 v0, s40, v6
	s_addc_u32 s3, s24, s3
	s_lshl_b64 s[4:5], s[4:5], 1
	v_med3_i32 v0, v0, 0, v211
	s_add_u32 s4, s34, s4
	v_cndmask_b32_e32 v0, v6, v0, vcc
	s_addc_u32 s5, s29, s5
	v_bfe_u32 v223, v175, 4, 2
	v_mad_u64_u32 v[166:167], s[28:29], v0, s14, 0
	v_xor_b32_e32 v4, v223, v175
	v_ashrrev_i32_e32 v2, 31, v0
	v_mov_b32_e32 v0, v167
	v_mad_u64_u32 v[2:3], s[28:29], v2, s14, v[0:1]
	v_lshlrev_b32_e32 v0, 3, v4
	v_lshlrev_b32_e32 v15, 2, v10
	v_and_b32_e32 v0, 56, v0
	v_lshlrev_b32_e32 v177, 12, v10
	v_lshlrev_b32_e32 v130, 1, v0
	v_ashrrev_i32_e32 v0, 31, v10
	v_or_b32_e32 v17, v176, v177
	v_or_b32_e32 v18, 1, v15
	v_and_b32_e32 v174, 3, v10
	v_mul_lo_u32 v16, v0, s14
	v_readfirstlane_b32 s15, v17
	v_add_u32_e32 v0, 0x8000, v17
	v_lshl_or_b32 v10, v18, 3, v14
	v_mov_b32_e32 v167, v2
	v_mad_u64_u32 v[168:169], s[28:29], v6, s14, 0
	s_mov_b32 m0, s15
	v_readfirstlane_b32 s15, v0
	v_add_u32_e32 v0, s40, v10
	v_lshl_add_u64 v[2:3], v[166:167], 1, s[2:3]
	v_mov_b32_e32 v131, v1
	v_add_u32_e32 v169, v169, v16
	v_med3_i32 v0, v0, 0, v211
	v_lshl_add_u64 v[4:5], v[2:3], 0, v[130:131]
	v_lshl_add_u64 v[6:7], v[168:169], 1, s[4:5]
	v_cndmask_b32_e32 v0, v10, v0, vcc
	v_lshl_add_u64 v[8:9], v[6:7], 0, v[130:131]
	global_load_lds_dwordx4 v[4:5], off
	s_mov_b32 m0, s15
	v_lshrrev_b32_e32 v4, 1, v10
	v_mad_u64_u32 v[170:171], s[28:29], v0, s14, 0
	global_load_lds_dwordx4 v[8:9], off
	v_xor_b32_e32 v8, v4, v175
	v_ashrrev_i32_e32 v4, 31, v0
	v_mov_b32_e32 v0, v171
	v_mad_u64_u32 v[4:5], s[28:29], v4, s14, v[0:1]
	v_lshlrev_b32_e32 v0, 3, v8
	v_lshlrev_b32_e32 v178, 10, v18
	v_mov_b32_e32 v171, v4
	v_and_b32_e32 v0, 56, v0
	v_mad_u64_u32 v[172:173], s[28:29], v10, s14, 0
	v_or_b32_e32 v18, v176, v178
	v_lshl_add_u64 v[4:5], v[170:171], 1, s[2:3]
	v_lshlrev_b32_e32 v132, 1, v0
	v_mov_b32_e32 v133, v1
	v_add_u32_e32 v173, v173, v16
	v_readfirstlane_b32 s15, v18
	v_add_u32_e32 v0, 0x8000, v18
	v_lshl_add_u64 v[8:9], v[4:5], 0, v[132:133]
	v_lshl_add_u64 v[10:11], v[172:173], 1, s[4:5]
	s_mov_b32 m0, s15
	v_readfirstlane_b32 s15, v0
	s_waitcnt lgkmcnt(0)
	v_lshl_add_u64 v[12:13], v[10:11], 0, v[132:133]
	global_load_lds_dwordx4 v[8:9], off
	s_mov_b32 m0, s15
	v_or_b32_e32 v19, 2, v15
	global_load_lds_dwordx4 v[12:13], off
	v_lshl_or_b32 v12, v19, 3, v14
	v_add_u32_e32 v0, s40, v12
	v_med3_i32 v0, v0, 0, v211
	v_cndmask_b32_e32 v0, v12, v0, vcc
	v_lshrrev_b32_e32 v8, 1, v12
	v_mad_u64_u32 v[154:155], s[28:29], v0, s14, 0
	v_xor_b32_e32 v13, v8, v175
	v_ashrrev_i32_e32 v8, 31, v0
	v_mov_b32_e32 v0, v155
	v_mad_u64_u32 v[8:9], s[28:29], v8, s14, v[0:1]
	v_lshlrev_b32_e32 v0, 3, v13
	v_lshlrev_b32_e32 v179, 10, v19
	v_mov_b32_e32 v155, v8
	v_and_b32_e32 v0, 56, v0
	v_or_b32_e32 v19, v176, v179
	v_lshl_add_u64 v[8:9], v[154:155], 1, s[2:3]
	v_lshlrev_b32_e32 v0, 1, v0
	v_readfirstlane_b32 s15, v19
	v_lshl_add_u64 v[8:9], v[8:9], 0, v[0:1]
	v_mad_u64_u32 v[156:157], s[28:29], v12, s14, 0
	s_mov_b32 m0, s15
	v_add_u32_e32 v157, v157, v16
	global_load_lds_dwordx4 v[8:9], off
	v_add_u32_e32 v8, 0x8000, v19
	v_lshl_add_u64 v[12:13], v[156:157], 1, s[4:5]
	v_readfirstlane_b32 s15, v8
	v_lshl_add_u64 v[12:13], v[12:13], 0, v[0:1]
	s_mov_b32 m0, s15
	v_or_b32_e32 v15, 3, v15
	global_load_lds_dwordx4 v[12:13], off
	v_lshl_or_b32 v12, v15, 3, v14
	v_add_u32_e32 v8, s40, v12
	v_med3_i32 v8, v8, 0, v211
	v_cndmask_b32_e32 v8, v12, v8, vcc
	v_lshrrev_b32_e32 v9, 1, v12
	v_mad_u64_u32 v[158:159], s[28:29], v8, s14, 0
	v_xor_b32_e32 v13, v9, v175
	v_ashrrev_i32_e32 v9, 31, v8
	v_mov_b32_e32 v8, v159
	v_mad_u64_u32 v[8:9], s[28:29], v9, s14, v[8:9]
	v_lshlrev_b32_e32 v13, 3, v13
	v_lshlrev_b32_e32 v180, 10, v15
	v_mov_b32_e32 v159, v8
	v_and_b32_e32 v13, 56, v13
	v_or_b32_e32 v14, v176, v180
	v_lshl_add_u64 v[8:9], v[158:159], 1, s[2:3]
	v_lshlrev_b32_e32 v160, 1, v13
	v_mov_b32_e32 v161, v1
	v_readfirstlane_b32 s15, v14
	v_lshl_add_u64 v[8:9], v[8:9], 0, v[160:161]
	v_mad_u64_u32 v[164:165], s[28:29], v12, s14, 0
	s_mov_b32 m0, s15
	v_add_u32_e32 v165, v165, v16
	global_load_lds_dwordx4 v[8:9], off
	v_add_u32_e32 v8, 0x8000, v14
	s_cmpk_gt_u32 s14, 0x7f
	v_lshl_add_u64 v[12:13], v[164:165], 1, s[4:5]
	v_readfirstlane_b32 s15, v8
	s_cselect_b32 s34, 0x80, 0
	v_add_u32_e32 v8, 0x10000, v17
	v_lshl_add_u64 v[12:13], v[12:13], 0, v[160:161]
	s_mov_b32 m0, s15
	v_lshl_add_u64 v[2:3], v[2:3], 0, s[34:35]
	v_readfirstlane_b32 s15, v8
	global_load_lds_dwordx4 v[12:13], off
	v_lshl_add_u64 v[2:3], v[2:3], 0, v[130:131]
	s_mov_b32 m0, s15
	v_mov_b32_e32 v127, 0
	v_mov_b32_e32 v128, 0
	v_mov_b32_e32 v129, 0
	v_mov_b32_e32 v122, 0
	v_mov_b32_e32 v123, 0
	v_mov_b32_e32 v124, 0
	v_mov_b32_e32 v125, 0
	v_mov_b32_e32 v118, 0
	v_mov_b32_e32 v119, 0
	v_mov_b32_e32 v120, 0
	v_mov_b32_e32 v121, 0
	v_mov_b32_e32 v114, 0
	v_mov_b32_e32 v115, 0
	v_mov_b32_e32 v116, 0
	v_mov_b32_e32 v117, 0
	v_mov_b32_e32 v110, 0
	v_mov_b32_e32 v111, 0
	v_mov_b32_e32 v112, 0
	v_mov_b32_e32 v113, 0
	v_mov_b32_e32 v106, 0
	v_mov_b32_e32 v107, 0
	v_mov_b32_e32 v108, 0
	v_mov_b32_e32 v109, 0
	v_mov_b32_e32 v102, 0
	v_mov_b32_e32 v103, 0
	v_mov_b32_e32 v104, 0
	v_mov_b32_e32 v105, 0
	v_mov_b32_e32 v98, 0
	v_mov_b32_e32 v99, 0
	v_mov_b32_e32 v100, 0
	v_mov_b32_e32 v101, 0
	v_mov_b32_e32 v94, 0
	v_mov_b32_e32 v95, 0
	v_mov_b32_e32 v96, 0
	v_mov_b32_e32 v97, 0
	v_mov_b32_e32 v90, 0
	v_mov_b32_e32 v91, 0
	v_mov_b32_e32 v92, 0
	v_mov_b32_e32 v93, 0
	v_mov_b32_e32 v86, 0
	v_mov_b32_e32 v87, 0
	v_mov_b32_e32 v88, 0
	v_mov_b32_e32 v89, 0
	v_mov_b32_e32 v82, 0
	v_mov_b32_e32 v83, 0
	v_mov_b32_e32 v84, 0
	v_mov_b32_e32 v85, 0
	v_mov_b32_e32 v78, 0
	v_mov_b32_e32 v79, 0
	v_mov_b32_e32 v80, 0
	v_mov_b32_e32 v81, 0
	v_mov_b32_e32 v74, 0
	v_mov_b32_e32 v75, 0
	v_mov_b32_e32 v76, 0
	v_mov_b32_e32 v77, 0
	v_mov_b32_e32 v70, 0
	v_mov_b32_e32 v71, 0
	v_mov_b32_e32 v72, 0
	v_mov_b32_e32 v73, 0
	v_mov_b32_e32 v66, 0
	v_mov_b32_e32 v67, 0
	v_mov_b32_e32 v68, 0
	v_mov_b32_e32 v69, 0
	v_mov_b32_e32 v62, 0
	v_mov_b32_e32 v63, 0
	v_mov_b32_e32 v64, 0
	v_mov_b32_e32 v65, 0
	v_mov_b32_e32 v58, 0
	v_mov_b32_e32 v59, 0
	v_mov_b32_e32 v60, 0
	v_mov_b32_e32 v61, 0
	v_mov_b32_e32 v54, 0
	v_mov_b32_e32 v55, 0
	v_mov_b32_e32 v56, 0
	v_mov_b32_e32 v57, 0
	v_mov_b32_e32 v50, 0
	v_mov_b32_e32 v51, 0
	v_mov_b32_e32 v52, 0
	v_mov_b32_e32 v53, 0
	v_mov_b32_e32 v46, 0
	v_mov_b32_e32 v47, 0
	v_mov_b32_e32 v48, 0
	v_mov_b32_e32 v49, 0
	v_mov_b32_e32 v42, 0
	v_mov_b32_e32 v43, 0
	v_mov_b32_e32 v44, 0
	v_mov_b32_e32 v45, 0
	v_mov_b32_e32 v34, 0
	v_mov_b32_e32 v35, 0
	v_mov_b32_e32 v36, 0
	v_mov_b32_e32 v37, 0
	v_mov_b32_e32 v30, 0
	v_mov_b32_e32 v31, 0
	v_mov_b32_e32 v32, 0
	v_mov_b32_e32 v33, 0
	v_mov_b32_e32 v38, 0
	v_mov_b32_e32 v39, 0
	v_mov_b32_e32 v40, 0
	v_mov_b32_e32 v41, 0
	v_mov_b32_e32 v26, 0
	v_mov_b32_e32 v27, 0
	v_mov_b32_e32 v28, 0
	v_mov_b32_e32 v29, 0
	v_mov_b32_e32 v22, 0
	v_mov_b32_e32 v23, 0
	v_mov_b32_e32 v24, 0
	v_mov_b32_e32 v25, 0
	v_mov_b32_e32 v19, 0
	v_mov_b32_e32 v20, 0
	v_mov_b32_e32 v21, 0
	v_mov_b32_e32 v14, 0
	v_mov_b32_e32 v15, 0
	v_mov_b32_e32 v16, 0
	v_mov_b32_e32 v12, 0
	v_mov_b32_e32 v13, 0
	s_waitcnt vmcnt(0)
	s_waitcnt vmcnt(0) lgkmcnt(0)
	s_barrier
	global_load_lds_dwordx4 v[2:3], off
	v_add_u32_e32 v2, 0x18000, v17
	v_lshl_add_u64 v[6:7], v[6:7], 0, s[34:35]
	v_readfirstlane_b32 s15, v2
	v_lshl_add_u64 v[6:7], v[6:7], 0, v[130:131]
	s_mov_b32 m0, s15
	v_lshl_add_u64 v[2:3], v[4:5], 0, s[34:35]
	global_load_lds_dwordx4 v[6:7], off
	v_add_u32_e32 v6, 0x10000, v18
	v_lshl_add_u64 v[2:3], v[2:3], 0, v[132:133]
	v_readfirstlane_b32 s15, v6
	s_mov_b32 m0, s15
	v_lshl_add_u64 v[4:5], v[10:11], 0, s[34:35]
	global_load_lds_dwordx4 v[2:3], off
	v_add_u32_e32 v2, 0x18000, v18
	v_lshl_add_u64 v[4:5], v[4:5], 0, v[132:133]
	v_readfirstlane_b32 s15, v2
	s_mov_b32 m0, s15
	v_and_b32_e32 v134, 15, v175
	global_load_lds_dwordx4 v[4:5], off
	v_ashrrev_i32_e32 v2, 1, v175
	s_movk_i32 s15, 0xff80
	v_mov_b32_e32 v5, 0
	v_and_or_b32 v225, v2, s15, v134
	v_lshlrev_b32_e32 v224, 6, v174
	s_cmp_lt_u32 s14, 64
	v_readlane_b32 s51, v255, 37
	v_readlane_b32 s52, v255, 38
	s_cbranch_scc1 .Lgemm_skip_zero_a
	v_lshrrev_b32_e32 v10, 1, v134
	v_or_b32_e32 v2, v224, v134
	v_lshlrev_b32_e32 v182, 7, v2
	v_xor_b32_e32 v2, v223, v10
	v_lshlrev_b32_e32 v181, 7, v225
	v_lshlrev_b32_e32 v183, 4, v2
	v_or_b32_e32 v11, v181, v183
	v_or_b32_e32 v244, v182, v183
	v_lshl_add_u32 v240, v166, 1, v130
	v_lshl_add_u32 v241, v168, 1, v130
	v_lshl_add_u32 v242, v170, 1, v132
	v_lshl_add_u32 v243, v172, 1, v132
	ds_read_b128 v[150:153], v11
	ds_read_b128 v[146:149], v11 offset:2048
	ds_read_b128 v[142:145], v244 offset:32768
	ds_read_b128 v[138:141], v244 offset:34816
	ds_read_b128 v[134:137], v244 offset:36864
	ds_read_b128 v[200:203], v11 offset:4096
	ds_read_b128 v[130:133], v244 offset:38912
	ds_read_b128 v[236:239], v11 offset:6144
	s_lshr_b32 s14, s14, 6
	v_bitop3_b32 v10, v223, v10, 4 bitop3:0x36
	v_mov_b32_e32 v126, 0
	s_add_i32 s15, s14, -1
	v_lshlrev_b32_e32 v184, 4, v10
	s_mov_b32 s24, 0
	s_mov_b32 s28, 0
	v_mov_b32_e32 v161, v1
	v_lshl_add_u64 v[154:155], v[154:155], 1, v[0:1]
	v_lshl_add_u64 v[156:157], v[156:157], 1, v[0:1]
	v_lshl_add_u64 v[158:159], v[158:159], 1, v[160:161]
	v_lshl_add_u64 v[164:165], v[164:165], 1, v[160:161]
	v_readfirstlane_b32 s100, v179
	v_readfirstlane_b32 s101, v180
	v_readfirstlane_b32 s32, v178
	v_readfirstlane_b32 s41, v177
	s_lshl_b32 s32, s32, 16
	s_or_b32 s32, s32, s41
	v_readfirstlane_b32 s41, v163
	s_bitcmp1_b32 s41, 8
	s_cbranch_scc0 .Lgemm_prio_done
	s_setprio 1
.Lgemm_prio_done:
	v_mov_b32_e32 v18, v126
	v_mov_b32_e32 v17, v126
	v_mov_b32_e32 v10, v126
	v_mov_b32_e32 v11, v126
	v_mov_b32_e32 v6, v126
	v_mov_b32_e32 v7, v126
	v_mov_b32_e32 v8, v126
	v_mov_b32_e32 v9, v126
	v_mov_b32_e32 v2, v126
	v_mov_b32_e32 v3, v126
	v_mov_b32_e32 v4, v126
	v_mov_b32_e32 v5, v126

.LBB0_640:
	s_setprio 0
	s_and_b64 s[2:3], s[8:9], exec
	s_waitcnt vmcnt(0)
	v_readlane_b32 s2, v255, 15
	v_readlane_b32 s4, v255, 19
	v_readlane_b32 s3, v255, 16
	v_readlane_b32 s5, v255, 20
	s_cselect_b32 s42, s2, s4
	v_readlane_b32 s2, v255, 17
	s_cselect_b32 s28, s51, 0
	s_cselect_b32 s29, s52, 0
	s_cselect_b32 s43, s3, s5
	s_cselect_b32 s46, s2, 0
	s_cmp_lt_i32 s44, 4
	s_mov_b64 s[2:3], -1
	s_waitcnt vmcnt(0) lgkmcnt(0)
	s_barrier
	s_cbranch_scc1 .LBB0_1047
	s_cmp_lt_i32 s44, 6
	s_cbranch_scc1 .LBB0_1041
	s_cmp_gt_i32 s44, 6
	s_cbranch_scc0 .LBB0_654
	v_lshlrev_b32_e32 v244, 2, v175
	v_and_b32_e32 v244, 0x7c, v244
	v_lshl_or_b32 v244, s47, 7, v244
	v_lshlrev_b32_e32 v244, 2, v244
	v_readlane_b32 s100, v253, 61
	v_readlane_b32 s101, v253, 62
	s_mul_i32 s32, s28, 0x10800
	s_add_u32 s100, s100, s32
	s_mul_hi_u32 s32, s28, 0x10800
	s_addc_u32 s101, s101, s32
	v_readlane_b32 s4, v253, 63
	v_readlane_b32 s5, v254, 0
	s_mul_i32 s32, s28, 0x5800
	s_add_u32 s4, s4, s32
	s_mul_hi_u32 s32, s28, 0x5800
	s_addc_u32 s5, s5, s32
	v_add_u32_e32 v245, 0x5000, v244
	v_add_u32_e32 v246, 0xb000, v244
	v_add_u32_e32 v247, 0x8000, v244
	v_add_u32_e32 v226, 0xd000, v244
	v_add_u32_e32 v227, 0x2000, v244
	global_load_dwordx4 v[176:179], v244, s[100:101]
	global_load_dwordx4 v[180:183], v245, s[100:101] offset:2048
	global_load_dwordx4 v[184:187], v246, s[100:101]
	global_load_dwordx4 v[200:203], v227, s[100:101] offset:3072
	global_load_dwordx4 v[228:231], v247, s[100:101] offset:1024
	global_load_dwordx4 v[232:235], v226, s[100:101] offset:3072
	global_load_dwordx4 v[236:239], v244, s[4:5]
	global_load_dwordx4 v[240:243], v227, s[4:5] offset:3072
	s_movk_i32 s15, 0x210
	v_lshlrev_b32_e32 v0, 3, v223
	v_mul_lo_u32 v132, v225, s15
	v_cvt_pk_bf16_f32 v131, v128, v129
	v_cvt_pk_bf16_f32 v130, v126, v127
	v_add3_u32 v0, v224, v132, v0
	v_cvt_pk_bf16_f32 v133, v124, v125
	v_cvt_pk_bf16_f32 v132, v122, v123
	ds_write2_b64 v0, v[130:131], v[132:133] offset1:4
	v_cvt_pk_bf16_f32 v131, v120, v121
	v_cvt_pk_bf16_f32 v130, v118, v119
	v_cvt_pk_bf16_f32 v133, v116, v117
	v_cvt_pk_bf16_f32 v132, v114, v115
	ds_write2_b64 v0, v[130:131], v[132:133] offset0:32 offset1:36
	v_cvt_pk_bf16_f32 v131, v112, v113
	v_cvt_pk_bf16_f32 v130, v110, v111
	v_cvt_pk_bf16_f32 v133, v108, v109
	v_cvt_pk_bf16_f32 v132, v106, v107
	v_add_u32_e32 v134, 0x2000, v0
	ds_write2_b64 v134, v[130:131], v[132:133] offset0:32 offset1:36
	v_cvt_pk_bf16_f32 v131, v104, v105
	v_cvt_pk_bf16_f32 v130, v102, v103
	v_cvt_pk_bf16_f32 v133, v100, v101
	v_cvt_pk_bf16_f32 v132, v98, v99
	ds_write2_b64 v134, v[130:131], v[132:133] offset0:64 offset1:68
	v_cvt_pk_bf16_f32 v131, v96, v97
	v_cvt_pk_bf16_f32 v130, v94, v95
	v_cvt_pk_bf16_f32 v133, v92, v93
	v_cvt_pk_bf16_f32 v132, v90, v91
	v_add_u32_e32 v134, 0x4000, v0
	ds_write2_b64 v134, v[130:131], v[132:133] offset0:64 offset1:68
	v_cvt_pk_bf16_f32 v131, v88, v89
	v_cvt_pk_bf16_f32 v130, v86, v87
	v_cvt_pk_bf16_f32 v133, v84, v85
	v_cvt_pk_bf16_f32 v132, v82, v83
	ds_write2_b64 v134, v[130:131], v[132:133] offset0:96 offset1:100
	v_cvt_pk_bf16_f32 v131, v80, v81
	v_cvt_pk_bf16_f32 v130, v78, v79
	v_cvt_pk_bf16_f32 v133, v76, v77
	v_cvt_pk_bf16_f32 v132, v74, v75
	v_add_u32_e32 v134, 0x6000, v0
	ds_write2_b64 v134, v[130:131], v[132:133] offset0:96 offset1:100
	v_cvt_pk_bf16_f32 v131, v72, v73
	v_cvt_pk_bf16_f32 v130, v70, v71
	v_cvt_pk_bf16_f32 v133, v68, v69
	v_cvt_pk_bf16_f32 v132, v66, v67
	ds_write2_b64 v134, v[130:131], v[132:133] offset0:128 offset1:132
	v_cvt_pk_bf16_f32 v131, v64, v65
	v_cvt_pk_bf16_f32 v130, v62, v63
	v_cvt_pk_bf16_f32 v133, v60, v61
	v_cvt_pk_bf16_f32 v132, v58, v59
	v_add_u32_e32 v134, 0x8000, v0
	ds_write2_b64 v134, v[130:131], v[132:133] offset0:128 offset1:132
	v_cvt_pk_bf16_f32 v131, v56, v57
	v_cvt_pk_bf16_f32 v130, v54, v55
	v_cvt_pk_bf16_f32 v133, v52, v53
	v_cvt_pk_bf16_f32 v132, v50, v51
	ds_write2_b64 v134, v[130:131], v[132:133] offset0:160 offset1:164
	v_cvt_pk_bf16_f32 v131, v48, v49
	v_cvt_pk_bf16_f32 v130, v46, v47
	v_cvt_pk_bf16_f32 v133, v44, v45
	v_cvt_pk_bf16_f32 v132, v42, v43
	v_add_u32_e32 v134, 0xa000, v0
	ds_write2_b64 v134, v[130:131], v[132:133] offset0:160 offset1:164
	v_cvt_pk_bf16_f32 v131, v36, v37
	v_cvt_pk_bf16_f32 v130, v34, v35
	v_cvt_pk_bf16_f32 v133, v32, v33
	v_cvt_pk_bf16_f32 v132, v30, v31
	ds_write2_b64 v134, v[130:131], v[132:133] offset0:192 offset1:196
	v_cvt_pk_bf16_f32 v131, v40, v41
	v_cvt_pk_bf16_f32 v130, v38, v39
	v_cvt_pk_bf16_f32 v133, v28, v29
	v_cvt_pk_bf16_f32 v132, v26, v27
	v_add_u32_e32 v134, 0xc000, v0
	ds_write2_b64 v134, v[130:131], v[132:133] offset0:192 offset1:196
	v_cvt_pk_bf16_f32 v131, v24, v25
	v_cvt_pk_bf16_f32 v130, v22, v23
	v_cvt_pk_bf16_f32 v133, v20, v21
	v_cvt_pk_bf16_f32 v132, v18, v19
	ds_write2_b64 v134, v[130:131], v[132:133] offset0:224 offset1:228
	v_cvt_pk_bf16_f32 v131, v16, v17
	v_cvt_pk_bf16_f32 v130, v14, v15
	v_cvt_pk_bf16_f32 v133, v12, v13
	v_cvt_pk_bf16_f32 v132, v10, v11
	v_add_u32_e32 v134, 0xe000, v0
	ds_write2_b64 v134, v[130:131], v[132:133] offset0:224 offset1:228
	v_cvt_pk_bf16_f32 v131, v8, v9
	v_cvt_pk_bf16_f32 v130, v6, v7
	v_cvt_pk_bf16_f32 v133, v4, v5
	v_cvt_pk_bf16_f32 v132, v2, v3
	v_add_u32_e32 v0, 0xe800, v0
	ds_write2_b64 v0, v[130:131], v[132:133] offset1:4
	v_lshlrev_b32_e32 v0, 2, v175
	v_and_b32_e32 v0, 0x7c, v0
	s_mul_i32 s2, s28, 0x10800
	v_readlane_b32 s48, v253, 61
	v_lshl_or_b32 v164, s47, 7, v0
	s_mul_hi_u32 s3, s28, 0x10800
	v_readlane_b32 s49, v253, 62
	s_add_u32 s2, s48, s2
	v_ashrrev_i32_e32 v165, 31, v164
	s_addc_u32 s3, s49, s3
	v_lshlrev_b64 v[130:131], 2, v[164:165]
	v_lshl_add_u64 v[150:151], s[2:3], 0, v[130:131]
	s_movk_i32 s2, 0x5000
	v_add_co_u32_e32 v134, vcc, s2, v150
	s_mov_b32 s2, 0xb000
	s_nop 0
	v_addc_co_u32_e32 v135, vcc, 0, v151, vcc
	v_add_co_u32_e32 v138, vcc, s2, v150
	v_readlane_b32 s50, v253, 63
	s_nop 0
	v_addc_co_u32_e32 v139, vcc, 0, v151, vcc
	v_add_co_u32_e32 v142, vcc, s25, v150
	s_mul_i32 s4, s28, 0x5800
	s_nop 0
	v_addc_co_u32_e32 v143, vcc, 0, v151, vcc
	s_mov_b32 s2, 0x8000
	v_readlane_b32 s51, v254, 0
	s_mul_hi_u32 s5, s28, 0x5800
	s_add_u32 s4, s50, s4
	v_add_co_u32_e32 v146, vcc, s2, v150
	s_addc_u32 s5, s51, s5
	s_nop 0
	v_addc_co_u32_e32 v147, vcc, 0, v151, vcc
	s_mov_b32 s2, 0xd000
	s_waitcnt lgkmcnt(0)
	s_barrier
	v_lshl_add_u64 v[158:159], s[4:5], 0, v[130:131]
	s_waitcnt vmcnt(0)
	v_mov_b64_e32 v[130:131], v[176:177]
	v_mov_b64_e32 v[132:133], v[178:179]
	v_add_co_u32_e32 v150, vcc, s2, v150
	v_mov_b64_e32 v[134:135], v[180:181]
	v_mov_b64_e32 v[136:137], v[182:183]
	s_nop 0
	v_mov_b64_e32 v[138:139], v[184:185]
	v_mov_b64_e32 v[140:141], v[186:187]
	v_addc_co_u32_e32 v151, vcc, 0, v151, vcc
	v_mov_b64_e32 v[142:143], v[200:201]
	v_mov_b64_e32 v[144:145], v[202:203]
	s_nop 0
	v_mov_b64_e32 v[146:147], v[228:229]
	v_mov_b64_e32 v[148:149], v[230:231]
	s_nop 0
	v_mov_b64_e32 v[150:151], v[232:233]
	v_mov_b64_e32 v[152:153], v[234:235]
	s_nop 0
	v_mov_b64_e32 v[154:155], v[236:237]
	v_mov_b64_e32 v[156:157], v[238:239]
	v_add_co_u32_e32 v158, vcc, 0x2000, v158
	v_ashrrev_i32_e32 v0, 5, v175
	s_nop 0
	v_addc_co_u32_e32 v159, vcc, 0, v159, vcc
	v_mov_b64_e32 v[158:159], v[240:241]
	v_mov_b64_e32 v[160:161], v[242:243]
	v_readlane_b32 s2, v252, 32
	v_readlane_b32 s3, v252, 33
	v_mul_lo_u32 v166, v0, s15
	v_and_b32_e32 v167, 31, v175
	s_mov_b32 s14, 0
	v_lshl_add_u64 v[164:165], v[164:165], 1, s[2:3]
	v_lshl_add_u32 v166, v167, 3, v166
	v_add_u32_e32 v167, s40, v0
	s_waitcnt vmcnt(0)
	s_mov_b32 s14, 0x8800
	v_mul_u32_u24_e32 v63, 0x2100, v0
	v_and_b32_e32 v64, 31, v175
	v_lshl_add_u32 v63, v64, 3, v63
	v_lshlrev_b32_e32 v61, 4, v0
	v_add_u32_e32 v61, 1, v61
	v_add_u32_e32 v62, s40, v61
	s_mov_b32 s4, 0x78787879
	v_mul_hi_i32 v60, v62, s4
	v_lshrrev_b32_e32 v64, 31, v60
	v_ashrrev_i32_e32 v60, 11, v60
	v_add_u32_e32 v60, v60, v64
	v_mul_i32_i24_e32 v60, 0x1100, v60
	v_sub_u32_e32 v60, v62, v60
	s_movk_i32 s4, 0x1600
	v_mad_i64_i32 v[58:59], s[4:5], v62, s4, v[164:165]
	v_mov_b32_e32 v56, 0x1600
	v_mov_b32_e32 v57, 0
	ds_read2_b64 v[26:29], v63 offset1:32
	ds_read2_b64 v[68:71], v63 offset0:66 offset1:98
	s_waitcnt lgkmcnt(0)
	v_lshlrev_b32_e32 v2, 16, v26
	v_and_b32_e32 v3, 0xffff0000, v26
	v_lshlrev_b32_e32 v4, 16, v27
	v_and_b32_e32 v5, 0xffff0000, v27
	v_lshlrev_b32_e32 v14, 16, v28
	v_and_b32_e32 v15, 0xffff0000, v28
	v_lshlrev_b32_e32 v16, 16, v29
	v_and_b32_e32 v17, 0xffff0000, v29
	v_lshlrev_b32_e32 v6, 16, v68
	v_and_b32_e32 v7, 0xffff0000, v68
	v_lshlrev_b32_e32 v8, 16, v69
	v_and_b32_e32 v9, 0xffff0000, v69
	v_lshlrev_b32_e32 v18, 16, v70
	v_and_b32_e32 v19, 0xffff0000, v70
	v_lshlrev_b32_e32 v20, 16, v71
	v_and_b32_e32 v21, 0xffff0000, v71
	v_add_u32_e32 v63, 0x420, v63
	v_add_u32_e32 v64, -1, v60
	v_add_u32_e32 v65, 0xfffffeff, v60
	v_cmp_gt_u32_e32 vcc, 0xfef, v65
	s_mov_b64 s[4:5], vcc
	v_cmp_gt_u32_e32 vcc, 0xef, v64
	s_or_b64 s[4:5], s[4:5], vcc
	v_add_u32_e32 v64, 15, v62
	v_cmp_gt_i32_e32 vcc, s14, v64
	s_and_b64 s[4:5], s[4:5], vcc
	s_xor_b64 s[4:5], s[4:5], exec
	s_cmp_eq_u64 s[4:5], 0
	s_cbranch_scc0 .Lconv_slow
	v_cmp_gt_u32_e32 vcc, 15, v0
	s_mov_b32 s6, 0xbfb8aa3b
	ds_read2_b64 v[26:29], v63 offset1:32
	s_waitcnt lgkmcnt(0)
	v_lshlrev_b32_e32 v10, 16, v26
	v_and_b32_e32 v11, 0xffff0000, v26
	v_lshlrev_b32_e32 v12, 16, v27
	v_and_b32_e32 v13, 0xffff0000, v27
	v_lshlrev_b32_e32 v22, 16, v28
	v_and_b32_e32 v23, 0xffff0000, v28
	v_lshlrev_b32_e32 v24, 16, v29
	v_and_b32_e32 v25, 0xffff0000, v29
	v_add_u32_e32 v63, 0x210, v63
	ds_read2_b64 v[26:29], v63 offset1:32
	v_pk_fma_f32 v[30:31], v[146:147], v[18:19], v[158:159]
	v_pk_fma_f32 v[32:33], v[148:149], v[20:21], v[160:161]
	v_pk_fma_f32 v[34:35], v[134:135], v[6:7], v[154:155]
	v_pk_fma_f32 v[36:37], v[136:137], v[8:9], v[156:157]
	v_pk_fma_f32 v[30:31], v[142:143], v[14:15], v[30:31]
	v_pk_fma_f32 v[32:33], v[144:145], v[16:17], v[32:33]
	v_pk_fma_f32 v[34:35], v[130:131], v[2:3], v[34:35]
	v_pk_fma_f32 v[36:37], v[132:133], v[4:5], v[36:37]
	v_pk_fma_f32 v[30:31], v[150:151], v[22:23], v[30:31]
	v_pk_fma_f32 v[32:33], v[152:153], v[24:25], v[32:33]
	v_pk_fma_f32 v[34:35], v[138:139], v[10:11], v[34:35]
	v_pk_fma_f32 v[36:37], v[140:141], v[12:13], v[36:37]
	v_pk_mul_f32 v[42:43], v[30:31], s[6:7] op_sel_hi:[1,0]
	v_pk_mul_f32 v[44:45], v[32:33], s[6:7] op_sel_hi:[1,0]
	v_exp_f32_e32 v42, v42
	v_exp_f32_e32 v43, v43
	v_exp_f32_e32 v44, v44
	v_exp_f32_e32 v45, v45
	v_pk_add_f32 v[42:43], v[42:43], 1.0 op_sel_hi:[1,0]
	v_pk_add_f32 v[44:45], v[44:45], 1.0 op_sel_hi:[1,0]
	v_rcp_f32_e32 v46, v42
	v_rcp_f32_e32 v47, v43
	v_rcp_f32_e32 v48, v44
	v_rcp_f32_e32 v49, v45
	v_pk_mul_f32 v[46:47], v[30:31], v[46:47]
	v_pk_mul_f32 v[48:49], v[32:33], v[48:49]
	v_pk_mul_f32 v[34:35], v[34:35], v[46:47]
	v_pk_mul_f32 v[36:37], v[36:37], v[48:49]
	v_cvt_pk_bf16_f32 v66, v34, v35
	v_cvt_pk_bf16_f32 v67, v36, v37
	global_store_dwordx2 v[58:59], v[66:67], off
	v_lshl_add_u64 v[58:59], v[58:59], 0, v[56:57]
	s_waitcnt lgkmcnt(0)
	v_lshlrev_b32_e32 v2, 16, v26
	v_and_b32_e32 v3, 0xffff0000, v26
	v_lshlrev_b32_e32 v4, 16, v27
	v_and_b32_e32 v5, 0xffff0000, v27
	v_lshlrev_b32_e32 v14, 16, v28
	v_and_b32_e32 v15, 0xffff0000, v28
	v_lshlrev_b32_e32 v16, 16, v29
	v_and_b32_e32 v17, 0xffff0000, v29
	v_add_u32_e32 v63, 0x210, v63
	ds_read2_b64 v[26:29], v63 offset1:32
	v_pk_fma_f32 v[30:31], v[146:147], v[22:23], v[158:159]
	v_pk_fma_f32 v[32:33], v[148:149], v[24:25], v[160:161]
	v_pk_fma_f32 v[34:35], v[134:135], v[10:11], v[154:155]
	v_pk_fma_f32 v[36:37], v[136:137], v[12:13], v[156:157]
	v_pk_fma_f32 v[30:31], v[142:143], v[18:19], v[30:31]
	v_pk_fma_f32 v[32:33], v[144:145], v[20:21], v[32:33]
	v_pk_fma_f32 v[34:35], v[130:131], v[6:7], v[34:35]
	v_pk_fma_f32 v[36:37], v[132:133], v[8:9], v[36:37]
	v_pk_fma_f32 v[30:31], v[150:151], v[14:15], v[30:31]
	v_pk_fma_f32 v[32:33], v[152:153], v[16:17], v[32:33]
	v_pk_fma_f32 v[34:35], v[138:139], v[2:3], v[34:35]
	v_pk_fma_f32 v[36:37], v[140:141], v[4:5], v[36:37]
	v_pk_mul_f32 v[42:43], v[30:31], s[6:7] op_sel_hi:[1,0]
	v_pk_mul_f32 v[44:45], v[32:33], s[6:7] op_sel_hi:[1,0]
	v_exp_f32_e32 v42, v42
	v_exp_f32_e32 v43, v43
	v_exp_f32_e32 v44, v44
	v_exp_f32_e32 v45, v45
	v_pk_add_f32 v[42:43], v[42:43], 1.0 op_sel_hi:[1,0]
	v_pk_add_f32 v[44:45], v[44:45], 1.0 op_sel_hi:[1,0]
	v_rcp_f32_e32 v46, v42
	v_rcp_f32_e32 v47, v43
	v_rcp_f32_e32 v48, v44
	v_rcp_f32_e32 v49, v45
	v_pk_mul_f32 v[46:47], v[30:31], v[46:47]
	v_pk_mul_f32 v[48:49], v[32:33], v[48:49]
	v_pk_mul_f32 v[34:35], v[34:35], v[46:47]
	v_pk_mul_f32 v[36:37], v[36:37], v[48:49]
	v_cvt_pk_bf16_f32 v66, v34, v35
	v_cvt_pk_bf16_f32 v67, v36, v37
	global_store_dwordx2 v[58:59], v[66:67], off
	v_lshl_add_u64 v[58:59], v[58:59], 0, v[56:57]
	s_waitcnt lgkmcnt(0)
	v_lshlrev_b32_e32 v6, 16, v26
	v_and_b32_e32 v7, 0xffff0000, v26
	v_lshlrev_b32_e32 v8, 16, v27
	v_and_b32_e32 v9, 0xffff0000, v27
	v_lshlrev_b32_e32 v18, 16, v28
	v_and_b32_e32 v19, 0xffff0000, v28
	v_lshlrev_b32_e32 v20, 16, v29
	v_and_b32_e32 v21, 0xffff0000, v29
	v_add_u32_e32 v63, 0x210, v63
	ds_read2_b64 v[26:29], v63 offset1:32
	v_pk_fma_f32 v[30:31], v[146:147], v[14:15], v[158:159]
	v_pk_fma_f32 v[32:33], v[148:149], v[16:17], v[160:161]
	v_pk_fma_f32 v[34:35], v[134:135], v[2:3], v[154:155]
	v_pk_fma_f32 v[36:37], v[136:137], v[4:5], v[156:157]
	v_pk_fma_f32 v[30:31], v[142:143], v[22:23], v[30:31]
	v_pk_fma_f32 v[32:33], v[144:145], v[24:25], v[32:33]
	v_pk_fma_f32 v[34:35], v[130:131], v[10:11], v[34:35]
	v_pk_fma_f32 v[36:37], v[132:133], v[12:13], v[36:37]
	v_pk_fma_f32 v[30:31], v[150:151], v[18:19], v[30:31]
	v_pk_fma_f32 v[32:33], v[152:153], v[20:21], v[32:33]
	v_pk_fma_f32 v[34:35], v[138:139], v[6:7], v[34:35]
	v_pk_fma_f32 v[36:37], v[140:141], v[8:9], v[36:37]
	v_pk_mul_f32 v[42:43], v[30:31], s[6:7] op_sel_hi:[1,0]
	v_pk_mul_f32 v[44:45], v[32:33], s[6:7] op_sel_hi:[1,0]
	v_exp_f32_e32 v42, v42
	v_exp_f32_e32 v43, v43
	v_exp_f32_e32 v44, v44
	v_exp_f32_e32 v45, v45
	v_pk_add_f32 v[42:43], v[42:43], 1.0 op_sel_hi:[1,0]
	v_pk_add_f32 v[44:45], v[44:45], 1.0 op_sel_hi:[1,0]
	v_rcp_f32_e32 v46, v42
	v_rcp_f32_e32 v47, v43
	v_rcp_f32_e32 v48, v44
	v_rcp_f32_e32 v49, v45
	v_pk_mul_f32 v[46:47], v[30:31], v[46:47]
	v_pk_mul_f32 v[48:49], v[32:33], v[48:49]
	v_pk_mul_f32 v[34:35], v[34:35], v[46:47]
	v_pk_mul_f32 v[36:37], v[36:37], v[48:49]
	v_cvt_pk_bf16_f32 v66, v34, v35
	v_cvt_pk_bf16_f32 v67, v36, v37
	global_store_dwordx2 v[58:59], v[66:67], off
	v_lshl_add_u64 v[58:59], v[58:59], 0, v[56:57]
	s_waitcnt lgkmcnt(0)
	v_lshlrev_b32_e32 v10, 16, v26
	v_and_b32_e32 v11, 0xffff0000, v26
	v_lshlrev_b32_e32 v12, 16, v27
	v_and_b32_e32 v13, 0xffff0000, v27
	v_lshlrev_b32_e32 v22, 16, v28
	v_and_b32_e32 v23, 0xffff0000, v28
	v_lshlrev_b32_e32 v24, 16, v29
	v_and_b32_e32 v25, 0xffff0000, v29
	v_add_u32_e32 v63, 0x210, v63
	ds_read2_b64 v[26:29], v63 offset1:32
	v_pk_fma_f32 v[30:31], v[146:147], v[18:19], v[158:159]
	v_pk_fma_f32 v[32:33], v[148:149], v[20:21], v[160:161]
	v_pk_fma_f32 v[34:35], v[134:135], v[6:7], v[154:155]
	v_pk_fma_f32 v[36:37], v[136:137], v[8:9], v[156:157]
	v_pk_fma_f32 v[30:31], v[142:143], v[14:15], v[30:31]
	v_pk_fma_f32 v[32:33], v[144:145], v[16:17], v[32:33]
	v_pk_fma_f32 v[34:35], v[130:131], v[2:3], v[34:35]
	v_pk_fma_f32 v[36:37], v[132:133], v[4:5], v[36:37]
	v_pk_fma_f32 v[30:31], v[150:151], v[22:23], v[30:31]
	v_pk_fma_f32 v[32:33], v[152:153], v[24:25], v[32:33]
	v_pk_fma_f32 v[34:35], v[138:139], v[10:11], v[34:35]
	v_pk_fma_f32 v[36:37], v[140:141], v[12:13], v[36:37]
	v_pk_mul_f32 v[42:43], v[30:31], s[6:7] op_sel_hi:[1,0]
	v_pk_mul_f32 v[44:45], v[32:33], s[6:7] op_sel_hi:[1,0]
	v_exp_f32_e32 v42, v42
	v_exp_f32_e32 v43, v43
	v_exp_f32_e32 v44, v44
	v_exp_f32_e32 v45, v45
	v_pk_add_f32 v[42:43], v[42:43], 1.0 op_sel_hi:[1,0]
	v_pk_add_f32 v[44:45], v[44:45], 1.0 op_sel_hi:[1,0]
	v_rcp_f32_e32 v46, v42
	v_rcp_f32_e32 v47, v43
	v_rcp_f32_e32 v48, v44
	v_rcp_f32_e32 v49, v45
	v_pk_mul_f32 v[46:47], v[30:31], v[46:47]
	v_pk_mul_f32 v[48:49], v[32:33], v[48:49]
	v_pk_mul_f32 v[34:35], v[34:35], v[46:47]
	v_pk_mul_f32 v[36:37], v[36:37], v[48:49]
	v_cvt_pk_bf16_f32 v66, v34, v35
	v_cvt_pk_bf16_f32 v67, v36, v37
	global_store_dwordx2 v[58:59], v[66:67], off
	v_lshl_add_u64 v[58:59], v[58:59], 0, v[56:57]
	s_waitcnt lgkmcnt(0)
	v_lshlrev_b32_e32 v2, 16, v26
	v_and_b32_e32 v3, 0xffff0000, v26
	v_lshlrev_b32_e32 v4, 16, v27
	v_and_b32_e32 v5, 0xffff0000, v27
	v_lshlrev_b32_e32 v14, 16, v28
	v_and_b32_e32 v15, 0xffff0000, v28
	v_lshlrev_b32_e32 v16, 16, v29
	v_and_b32_e32 v17, 0xffff0000, v29
	v_add_u32_e32 v63, 0x210, v63
	ds_read2_b64 v[26:29], v63 offset1:32
	v_pk_fma_f32 v[30:31], v[146:147], v[22:23], v[158:159]
	v_pk_fma_f32 v[32:33], v[148:149], v[24:25], v[160:161]
	v_pk_fma_f32 v[34:35], v[134:135], v[10:11], v[154:155]
	v_pk_fma_f32 v[36:37], v[136:137], v[12:13], v[156:157]
	v_pk_fma_f32 v[30:31], v[142:143], v[18:19], v[30:31]
	v_pk_fma_f32 v[32:33], v[144:145], v[20:21], v[32:33]
	v_pk_fma_f32 v[34:35], v[130:131], v[6:7], v[34:35]
	v_pk_fma_f32 v[36:37], v[132:133], v[8:9], v[36:37]
	v_pk_fma_f32 v[30:31], v[150:151], v[14:15], v[30:31]
	v_pk_fma_f32 v[32:33], v[152:153], v[16:17], v[32:33]
	v_pk_fma_f32 v[34:35], v[138:139], v[2:3], v[34:35]
	v_pk_fma_f32 v[36:37], v[140:141], v[4:5], v[36:37]
	v_pk_mul_f32 v[42:43], v[30:31], s[6:7] op_sel_hi:[1,0]
	v_pk_mul_f32 v[44:45], v[32:33], s[6:7] op_sel_hi:[1,0]
	v_exp_f32_e32 v42, v42
	v_exp_f32_e32 v43, v43
	v_exp_f32_e32 v44, v44
	v_exp_f32_e32 v45, v45
	v_pk_add_f32 v[42:43], v[42:43], 1.0 op_sel_hi:[1,0]
	v_pk_add_f32 v[44:45], v[44:45], 1.0 op_sel_hi:[1,0]
	v_rcp_f32_e32 v46, v42
	v_rcp_f32_e32 v47, v43
	v_rcp_f32_e32 v48, v44
	v_rcp_f32_e32 v49, v45
	v_pk_mul_f32 v[46:47], v[30:31], v[46:47]
	v_pk_mul_f32 v[48:49], v[32:33], v[48:49]
	v_pk_mul_f32 v[34:35], v[34:35], v[46:47]
	v_pk_mul_f32 v[36:37], v[36:37], v[48:49]
	v_cvt_pk_bf16_f32 v66, v34, v35
	v_cvt_pk_bf16_f32 v67, v36, v37
	global_store_dwordx2 v[58:59], v[66:67], off
	v_lshl_add_u64 v[58:59], v[58:59], 0, v[56:57]
	s_waitcnt lgkmcnt(0)
	v_lshlrev_b32_e32 v6, 16, v26
	v_and_b32_e32 v7, 0xffff0000, v26
	v_lshlrev_b32_e32 v8, 16, v27
	v_and_b32_e32 v9, 0xffff0000, v27
	v_lshlrev_b32_e32 v18, 16, v28
	v_and_b32_e32 v19, 0xffff0000, v28
	v_lshlrev_b32_e32 v20, 16, v29
	v_and_b32_e32 v21, 0xffff0000, v29
	v_add_u32_e32 v63, 0x210, v63
	ds_read2_b64 v[26:29], v63 offset1:32
	v_pk_fma_f32 v[30:31], v[146:147], v[14:15], v[158:159]
	v_pk_fma_f32 v[32:33], v[148:149], v[16:17], v[160:161]
	v_pk_fma_f32 v[34:35], v[134:135], v[2:3], v[154:155]
	v_pk_fma_f32 v[36:37], v[136:137], v[4:5], v[156:157]
	v_pk_fma_f32 v[30:31], v[142:143], v[22:23], v[30:31]
	v_pk_fma_f32 v[32:33], v[144:145], v[24:25], v[32:33]
	v_pk_fma_f32 v[34:35], v[130:131], v[10:11], v[34:35]
	v_pk_fma_f32 v[36:37], v[132:133], v[12:13], v[36:37]
	v_pk_fma_f32 v[30:31], v[150:151], v[18:19], v[30:31]
	v_pk_fma_f32 v[32:33], v[152:153], v[20:21], v[32:33]
	v_pk_fma_f32 v[34:35], v[138:139], v[6:7], v[34:35]
	v_pk_fma_f32 v[36:37], v[140:141], v[8:9], v[36:37]
	v_pk_mul_f32 v[42:43], v[30:31], s[6:7] op_sel_hi:[1,0]
	v_pk_mul_f32 v[44:45], v[32:33], s[6:7] op_sel_hi:[1,0]
	v_exp_f32_e32 v42, v42
	v_exp_f32_e32 v43, v43
	v_exp_f32_e32 v44, v44
	v_exp_f32_e32 v45, v45
	v_pk_add_f32 v[42:43], v[42:43], 1.0 op_sel_hi:[1,0]
	v_pk_add_f32 v[44:45], v[44:45], 1.0 op_sel_hi:[1,0]
	v_rcp_f32_e32 v46, v42
	v_rcp_f32_e32 v47, v43
	v_rcp_f32_e32 v48, v44
	v_rcp_f32_e32 v49, v45
	v_pk_mul_f32 v[46:47], v[30:31], v[46:47]
	v_pk_mul_f32 v[48:49], v[32:33], v[48:49]
	v_pk_mul_f32 v[34:35], v[34:35], v[46:47]
	v_pk_mul_f32 v[36:37], v[36:37], v[48:49]
	v_cvt_pk_bf16_f32 v66, v34, v35
	v_cvt_pk_bf16_f32 v67, v36, v37
	global_store_dwordx2 v[58:59], v[66:67], off
	v_lshl_add_u64 v[58:59], v[58:59], 0, v[56:57]
	s_waitcnt lgkmcnt(0)
	v_lshlrev_b32_e32 v10, 16, v26
	v_and_b32_e32 v11, 0xffff0000, v26
	v_lshlrev_b32_e32 v12, 16, v27
	v_and_b32_e32 v13, 0xffff0000, v27
	v_lshlrev_b32_e32 v22, 16, v28
	v_and_b32_e32 v23, 0xffff0000, v28
	v_lshlrev_b32_e32 v24, 16, v29
	v_and_b32_e32 v25, 0xffff0000, v29
	v_add_u32_e32 v63, 0x210, v63
	ds_read2_b64 v[26:29], v63 offset1:32
	v_pk_fma_f32 v[30:31], v[146:147], v[18:19], v[158:159]
	v_pk_fma_f32 v[32:33], v[148:149], v[20:21], v[160:161]
	v_pk_fma_f32 v[34:35], v[134:135], v[6:7], v[154:155]
	v_pk_fma_f32 v[36:37], v[136:137], v[8:9], v[156:157]
	v_pk_fma_f32 v[30:31], v[142:143], v[14:15], v[30:31]
	v_pk_fma_f32 v[32:33], v[144:145], v[16:17], v[32:33]
	v_pk_fma_f32 v[34:35], v[130:131], v[2:3], v[34:35]
	v_pk_fma_f32 v[36:37], v[132:133], v[4:5], v[36:37]
	v_pk_fma_f32 v[30:31], v[150:151], v[22:23], v[30:31]
	v_pk_fma_f32 v[32:33], v[152:153], v[24:25], v[32:33]
	v_pk_fma_f32 v[34:35], v[138:139], v[10:11], v[34:35]
	v_pk_fma_f32 v[36:37], v[140:141], v[12:13], v[36:37]
	v_pk_mul_f32 v[42:43], v[30:31], s[6:7] op_sel_hi:[1,0]
	v_pk_mul_f32 v[44:45], v[32:33], s[6:7] op_sel_hi:[1,0]
	v_exp_f32_e32 v42, v42
	v_exp_f32_e32 v43, v43
	v_exp_f32_e32 v44, v44
	v_exp_f32_e32 v45, v45
	v_pk_add_f32 v[42:43], v[42:43], 1.0 op_sel_hi:[1,0]
	v_pk_add_f32 v[44:45], v[44:45], 1.0 op_sel_hi:[1,0]
	v_rcp_f32_e32 v46, v42
	v_rcp_f32_e32 v47, v43
	v_rcp_f32_e32 v48, v44
	v_rcp_f32_e32 v49, v45
	v_pk_mul_f32 v[46:47], v[30:31], v[46:47]
	v_pk_mul_f32 v[48:49], v[32:33], v[48:49]
	v_pk_mul_f32 v[34:35], v[34:35], v[46:47]
	v_pk_mul_f32 v[36:37], v[36:37], v[48:49]
	v_cvt_pk_bf16_f32 v66, v34, v35
	v_cvt_pk_bf16_f32 v67, v36, v37
	global_store_dwordx2 v[58:59], v[66:67], off
	v_lshl_add_u64 v[58:59], v[58:59], 0, v[56:57]
	s_waitcnt lgkmcnt(0)
	v_lshlrev_b32_e32 v2, 16, v26
	v_and_b32_e32 v3, 0xffff0000, v26
	v_lshlrev_b32_e32 v4, 16, v27
	v_and_b32_e32 v5, 0xffff0000, v27
	v_lshlrev_b32_e32 v14, 16, v28
	v_and_b32_e32 v15, 0xffff0000, v28
	v_lshlrev_b32_e32 v16, 16, v29
	v_and_b32_e32 v17, 0xffff0000, v29
	v_add_u32_e32 v63, 0x210, v63
	ds_read2_b64 v[26:29], v63 offset1:32
	v_pk_fma_f32 v[30:31], v[146:147], v[22:23], v[158:159]
	v_pk_fma_f32 v[32:33], v[148:149], v[24:25], v[160:161]
	v_pk_fma_f32 v[34:35], v[134:135], v[10:11], v[154:155]
	v_pk_fma_f32 v[36:37], v[136:137], v[12:13], v[156:157]
	v_pk_fma_f32 v[30:31], v[142:143], v[18:19], v[30:31]
	v_pk_fma_f32 v[32:33], v[144:145], v[20:21], v[32:33]
	v_pk_fma_f32 v[34:35], v[130:131], v[6:7], v[34:35]
	v_pk_fma_f32 v[36:37], v[132:133], v[8:9], v[36:37]
	v_pk_fma_f32 v[30:31], v[150:151], v[14:15], v[30:31]
	v_pk_fma_f32 v[32:33], v[152:153], v[16:17], v[32:33]
	v_pk_fma_f32 v[34:35], v[138:139], v[2:3], v[34:35]
	v_pk_fma_f32 v[36:37], v[140:141], v[4:5], v[36:37]
	v_pk_mul_f32 v[42:43], v[30:31], s[6:7] op_sel_hi:[1,0]
	v_pk_mul_f32 v[44:45], v[32:33], s[6:7] op_sel_hi:[1,0]
	v_exp_f32_e32 v42, v42
	v_exp_f32_e32 v43, v43
	v_exp_f32_e32 v44, v44
	v_exp_f32_e32 v45, v45
	v_pk_add_f32 v[42:43], v[42:43], 1.0 op_sel_hi:[1,0]
	v_pk_add_f32 v[44:45], v[44:45], 1.0 op_sel_hi:[1,0]
	v_rcp_f32_e32 v46, v42
	v_rcp_f32_e32 v47, v43
	v_rcp_f32_e32 v48, v44
	v_rcp_f32_e32 v49, v45
	v_pk_mul_f32 v[46:47], v[30:31], v[46:47]
	v_pk_mul_f32 v[48:49], v[32:33], v[48:49]
	v_pk_mul_f32 v[34:35], v[34:35], v[46:47]
	v_pk_mul_f32 v[36:37], v[36:37], v[48:49]
	v_cvt_pk_bf16_f32 v66, v34, v35
	v_cvt_pk_bf16_f32 v67, v36, v37
	global_store_dwordx2 v[58:59], v[66:67], off
	v_lshl_add_u64 v[58:59], v[58:59], 0, v[56:57]
	s_waitcnt lgkmcnt(0)
	v_lshlrev_b32_e32 v6, 16, v26
	v_and_b32_e32 v7, 0xffff0000, v26
	v_lshlrev_b32_e32 v8, 16, v27
	v_and_b32_e32 v9, 0xffff0000, v27
	v_lshlrev_b32_e32 v18, 16, v28
	v_and_b32_e32 v19, 0xffff0000, v28
	v_lshlrev_b32_e32 v20, 16, v29
	v_and_b32_e32 v21, 0xffff0000, v29
	v_add_u32_e32 v63, 0x210, v63
	ds_read2_b64 v[26:29], v63 offset1:32
	v_pk_fma_f32 v[30:31], v[146:147], v[14:15], v[158:159]
	v_pk_fma_f32 v[32:33], v[148:149], v[16:17], v[160:161]
	v_pk_fma_f32 v[34:35], v[134:135], v[2:3], v[154:155]
	v_pk_fma_f32 v[36:37], v[136:137], v[4:5], v[156:157]
	v_pk_fma_f32 v[30:31], v[142:143], v[22:23], v[30:31]
	v_pk_fma_f32 v[32:33], v[144:145], v[24:25], v[32:33]
	v_pk_fma_f32 v[34:35], v[130:131], v[10:11], v[34:35]
	v_pk_fma_f32 v[36:37], v[132:133], v[12:13], v[36:37]
	v_pk_fma_f32 v[30:31], v[150:151], v[18:19], v[30:31]
	v_pk_fma_f32 v[32:33], v[152:153], v[20:21], v[32:33]
	v_pk_fma_f32 v[34:35], v[138:139], v[6:7], v[34:35]
	v_pk_fma_f32 v[36:37], v[140:141], v[8:9], v[36:37]
	v_pk_mul_f32 v[42:43], v[30:31], s[6:7] op_sel_hi:[1,0]
	v_pk_mul_f32 v[44:45], v[32:33], s[6:7] op_sel_hi:[1,0]
	v_exp_f32_e32 v42, v42
	v_exp_f32_e32 v43, v43
	v_exp_f32_e32 v44, v44
	v_exp_f32_e32 v45, v45
	v_pk_add_f32 v[42:43], v[42:43], 1.0 op_sel_hi:[1,0]
	v_pk_add_f32 v[44:45], v[44:45], 1.0 op_sel_hi:[1,0]
	v_rcp_f32_e32 v46, v42
	v_rcp_f32_e32 v47, v43
	v_rcp_f32_e32 v48, v44
	v_rcp_f32_e32 v49, v45
	v_pk_mul_f32 v[46:47], v[30:31], v[46:47]
	v_pk_mul_f32 v[48:49], v[32:33], v[48:49]
	v_pk_mul_f32 v[34:35], v[34:35], v[46:47]
	v_pk_mul_f32 v[36:37], v[36:37], v[48:49]
	v_cvt_pk_bf16_f32 v66, v34, v35
	v_cvt_pk_bf16_f32 v67, v36, v37
	global_store_dwordx2 v[58:59], v[66:67], off
	v_lshl_add_u64 v[58:59], v[58:59], 0, v[56:57]
	s_waitcnt lgkmcnt(0)
	v_lshlrev_b32_e32 v10, 16, v26
	v_and_b32_e32 v11, 0xffff0000, v26
	v_lshlrev_b32_e32 v12, 16, v27
	v_and_b32_e32 v13, 0xffff0000, v27
	v_lshlrev_b32_e32 v22, 16, v28
	v_and_b32_e32 v23, 0xffff0000, v28
	v_lshlrev_b32_e32 v24, 16, v29
	v_and_b32_e32 v25, 0xffff0000, v29
	v_add_u32_e32 v63, 0x210, v63
	ds_read2_b64 v[26:29], v63 offset1:32
	v_pk_fma_f32 v[30:31], v[146:147], v[18:19], v[158:159]
	v_pk_fma_f32 v[32:33], v[148:149], v[20:21], v[160:161]
	v_pk_fma_f32 v[34:35], v[134:135], v[6:7], v[154:155]
	v_pk_fma_f32 v[36:37], v[136:137], v[8:9], v[156:157]
	v_pk_fma_f32 v[30:31], v[142:143], v[14:15], v[30:31]
	v_pk_fma_f32 v[32:33], v[144:145], v[16:17], v[32:33]
	v_pk_fma_f32 v[34:35], v[130:131], v[2:3], v[34:35]
	v_pk_fma_f32 v[36:37], v[132:133], v[4:5], v[36:37]
	v_pk_fma_f32 v[30:31], v[150:151], v[22:23], v[30:31]
	v_pk_fma_f32 v[32:33], v[152:153], v[24:25], v[32:33]
	v_pk_fma_f32 v[34:35], v[138:139], v[10:11], v[34:35]
	v_pk_fma_f32 v[36:37], v[140:141], v[12:13], v[36:37]
	v_pk_mul_f32 v[42:43], v[30:31], s[6:7] op_sel_hi:[1,0]
	v_pk_mul_f32 v[44:45], v[32:33], s[6:7] op_sel_hi:[1,0]
	v_exp_f32_e32 v42, v42
	v_exp_f32_e32 v43, v43
	v_exp_f32_e32 v44, v44
	v_exp_f32_e32 v45, v45
	v_pk_add_f32 v[42:43], v[42:43], 1.0 op_sel_hi:[1,0]
	v_pk_add_f32 v[44:45], v[44:45], 1.0 op_sel_hi:[1,0]
	v_rcp_f32_e32 v46, v42
	v_rcp_f32_e32 v47, v43
	v_rcp_f32_e32 v48, v44
	v_rcp_f32_e32 v49, v45
	v_pk_mul_f32 v[46:47], v[30:31], v[46:47]
	v_pk_mul_f32 v[48:49], v[32:33], v[48:49]
	v_pk_mul_f32 v[34:35], v[34:35], v[46:47]
	v_pk_mul_f32 v[36:37], v[36:37], v[48:49]
	v_cvt_pk_bf16_f32 v66, v34, v35
	v_cvt_pk_bf16_f32 v67, v36, v37
	global_store_dwordx2 v[58:59], v[66:67], off
	v_lshl_add_u64 v[58:59], v[58:59], 0, v[56:57]
	s_waitcnt lgkmcnt(0)
	v_lshlrev_b32_e32 v2, 16, v26
	v_and_b32_e32 v3, 0xffff0000, v26
	v_lshlrev_b32_e32 v4, 16, v27
	v_and_b32_e32 v5, 0xffff0000, v27
	v_lshlrev_b32_e32 v14, 16, v28
	v_and_b32_e32 v15, 0xffff0000, v28
	v_lshlrev_b32_e32 v16, 16, v29
	v_and_b32_e32 v17, 0xffff0000, v29
	v_add_u32_e32 v63, 0x210, v63
	ds_read2_b64 v[26:29], v63 offset1:32
	v_pk_fma_f32 v[30:31], v[146:147], v[22:23], v[158:159]
	v_pk_fma_f32 v[32:33], v[148:149], v[24:25], v[160:161]
	v_pk_fma_f32 v[34:35], v[134:135], v[10:11], v[154:155]
	v_pk_fma_f32 v[36:37], v[136:137], v[12:13], v[156:157]
	v_pk_fma_f32 v[30:31], v[142:143], v[18:19], v[30:31]
	v_pk_fma_f32 v[32:33], v[144:145], v[20:21], v[32:33]
	v_pk_fma_f32 v[34:35], v[130:131], v[6:7], v[34:35]
	v_pk_fma_f32 v[36:37], v[132:133], v[8:9], v[36:37]
	v_pk_fma_f32 v[30:31], v[150:151], v[14:15], v[30:31]
	v_pk_fma_f32 v[32:33], v[152:153], v[16:17], v[32:33]
	v_pk_fma_f32 v[34:35], v[138:139], v[2:3], v[34:35]
	v_pk_fma_f32 v[36:37], v[140:141], v[4:5], v[36:37]
	v_pk_mul_f32 v[42:43], v[30:31], s[6:7] op_sel_hi:[1,0]
	v_pk_mul_f32 v[44:45], v[32:33], s[6:7] op_sel_hi:[1,0]
	v_exp_f32_e32 v42, v42
	v_exp_f32_e32 v43, v43
	v_exp_f32_e32 v44, v44
	v_exp_f32_e32 v45, v45
	v_pk_add_f32 v[42:43], v[42:43], 1.0 op_sel_hi:[1,0]
	v_pk_add_f32 v[44:45], v[44:45], 1.0 op_sel_hi:[1,0]
	v_rcp_f32_e32 v46, v42
	v_rcp_f32_e32 v47, v43
	v_rcp_f32_e32 v48, v44
	v_rcp_f32_e32 v49, v45
	v_pk_mul_f32 v[46:47], v[30:31], v[46:47]
	v_pk_mul_f32 v[48:49], v[32:33], v[48:49]
	v_pk_mul_f32 v[34:35], v[34:35], v[46:47]
	v_pk_mul_f32 v[36:37], v[36:37], v[48:49]
	v_cvt_pk_bf16_f32 v66, v34, v35
	v_cvt_pk_bf16_f32 v67, v36, v37
	global_store_dwordx2 v[58:59], v[66:67], off
	v_lshl_add_u64 v[58:59], v[58:59], 0, v[56:57]
	s_waitcnt lgkmcnt(0)
	v_lshlrev_b32_e32 v6, 16, v26
	v_and_b32_e32 v7, 0xffff0000, v26
	v_lshlrev_b32_e32 v8, 16, v27
	v_and_b32_e32 v9, 0xffff0000, v27
	v_lshlrev_b32_e32 v18, 16, v28
	v_and_b32_e32 v19, 0xffff0000, v28
	v_lshlrev_b32_e32 v20, 16, v29
	v_and_b32_e32 v21, 0xffff0000, v29
	v_add_u32_e32 v63, 0x210, v63
	ds_read2_b64 v[26:29], v63 offset1:32
	v_pk_fma_f32 v[30:31], v[146:147], v[14:15], v[158:159]
	v_pk_fma_f32 v[32:33], v[148:149], v[16:17], v[160:161]
	v_pk_fma_f32 v[34:35], v[134:135], v[2:3], v[154:155]
	v_pk_fma_f32 v[36:37], v[136:137], v[4:5], v[156:157]
	v_pk_fma_f32 v[30:31], v[142:143], v[22:23], v[30:31]
	v_pk_fma_f32 v[32:33], v[144:145], v[24:25], v[32:33]
	v_pk_fma_f32 v[34:35], v[130:131], v[10:11], v[34:35]
	v_pk_fma_f32 v[36:37], v[132:133], v[12:13], v[36:37]
	v_pk_fma_f32 v[30:31], v[150:151], v[18:19], v[30:31]
	v_pk_fma_f32 v[32:33], v[152:153], v[20:21], v[32:33]
	v_pk_fma_f32 v[34:35], v[138:139], v[6:7], v[34:35]
	v_pk_fma_f32 v[36:37], v[140:141], v[8:9], v[36:37]
	v_pk_mul_f32 v[42:43], v[30:31], s[6:7] op_sel_hi:[1,0]
	v_pk_mul_f32 v[44:45], v[32:33], s[6:7] op_sel_hi:[1,0]
	v_exp_f32_e32 v42, v42
	v_exp_f32_e32 v43, v43
	v_exp_f32_e32 v44, v44
	v_exp_f32_e32 v45, v45
	v_pk_add_f32 v[42:43], v[42:43], 1.0 op_sel_hi:[1,0]
	v_pk_add_f32 v[44:45], v[44:45], 1.0 op_sel_hi:[1,0]
	v_rcp_f32_e32 v46, v42
	v_rcp_f32_e32 v47, v43
	v_rcp_f32_e32 v48, v44
	v_rcp_f32_e32 v49, v45
	v_pk_mul_f32 v[46:47], v[30:31], v[46:47]
	v_pk_mul_f32 v[48:49], v[32:33], v[48:49]
	v_pk_mul_f32 v[34:35], v[34:35], v[46:47]
	v_pk_mul_f32 v[36:37], v[36:37], v[48:49]
	v_cvt_pk_bf16_f32 v66, v34, v35
	v_cvt_pk_bf16_f32 v67, v36, v37
	global_store_dwordx2 v[58:59], v[66:67], off
	v_lshl_add_u64 v[58:59], v[58:59], 0, v[56:57]
	s_waitcnt lgkmcnt(0)
	v_lshlrev_b32_e32 v10, 16, v26
	v_and_b32_e32 v11, 0xffff0000, v26
	v_lshlrev_b32_e32 v12, 16, v27
	v_and_b32_e32 v13, 0xffff0000, v27
	v_lshlrev_b32_e32 v22, 16, v28
	v_and_b32_e32 v23, 0xffff0000, v28
	v_lshlrev_b32_e32 v24, 16, v29
	v_and_b32_e32 v25, 0xffff0000, v29
	v_add_u32_e32 v63, 0x210, v63
	ds_read2_b64 v[26:29], v63 offset1:32
	v_pk_fma_f32 v[30:31], v[146:147], v[18:19], v[158:159]
	v_pk_fma_f32 v[32:33], v[148:149], v[20:21], v[160:161]
	v_pk_fma_f32 v[34:35], v[134:135], v[6:7], v[154:155]
	v_pk_fma_f32 v[36:37], v[136:137], v[8:9], v[156:157]
	v_pk_fma_f32 v[30:31], v[142:143], v[14:15], v[30:31]
	v_pk_fma_f32 v[32:33], v[144:145], v[16:17], v[32:33]
	v_pk_fma_f32 v[34:35], v[130:131], v[2:3], v[34:35]
	v_pk_fma_f32 v[36:37], v[132:133], v[4:5], v[36:37]
	v_pk_fma_f32 v[30:31], v[150:151], v[22:23], v[30:31]
	v_pk_fma_f32 v[32:33], v[152:153], v[24:25], v[32:33]
	v_pk_fma_f32 v[34:35], v[138:139], v[10:11], v[34:35]
	v_pk_fma_f32 v[36:37], v[140:141], v[12:13], v[36:37]
	v_pk_mul_f32 v[42:43], v[30:31], s[6:7] op_sel_hi:[1,0]
	v_pk_mul_f32 v[44:45], v[32:33], s[6:7] op_sel_hi:[1,0]
	v_exp_f32_e32 v42, v42
	v_exp_f32_e32 v43, v43
	v_exp_f32_e32 v44, v44
	v_exp_f32_e32 v45, v45
	v_pk_add_f32 v[42:43], v[42:43], 1.0 op_sel_hi:[1,0]
	v_pk_add_f32 v[44:45], v[44:45], 1.0 op_sel_hi:[1,0]
	v_rcp_f32_e32 v46, v42
	v_rcp_f32_e32 v47, v43
	v_rcp_f32_e32 v48, v44
	v_rcp_f32_e32 v49, v45
	v_pk_mul_f32 v[46:47], v[30:31], v[46:47]
	v_pk_mul_f32 v[48:49], v[32:33], v[48:49]
	v_pk_mul_f32 v[34:35], v[34:35], v[46:47]
	v_pk_mul_f32 v[36:37], v[36:37], v[48:49]
	v_cvt_pk_bf16_f32 v66, v34, v35
	v_cvt_pk_bf16_f32 v67, v36, v37
	global_store_dwordx2 v[58:59], v[66:67], off
	v_lshl_add_u64 v[58:59], v[58:59], 0, v[56:57]
	s_waitcnt lgkmcnt(0)
	v_lshlrev_b32_e32 v2, 16, v26
	v_and_b32_e32 v3, 0xffff0000, v26
	v_lshlrev_b32_e32 v4, 16, v27
	v_and_b32_e32 v5, 0xffff0000, v27
	v_lshlrev_b32_e32 v14, 16, v28
	v_and_b32_e32 v15, 0xffff0000, v28
	v_lshlrev_b32_e32 v16, 16, v29
	v_and_b32_e32 v17, 0xffff0000, v29
	v_add_u32_e32 v63, 0x210, v63
	ds_read2_b64 v[26:29], v63 offset1:32
	v_pk_fma_f32 v[30:31], v[146:147], v[22:23], v[158:159]
	v_pk_fma_f32 v[32:33], v[148:149], v[24:25], v[160:161]
	v_pk_fma_f32 v[34:35], v[134:135], v[10:11], v[154:155]
	v_pk_fma_f32 v[36:37], v[136:137], v[12:13], v[156:157]
	v_pk_fma_f32 v[30:31], v[142:143], v[18:19], v[30:31]
	v_pk_fma_f32 v[32:33], v[144:145], v[20:21], v[32:33]
	v_pk_fma_f32 v[34:35], v[130:131], v[6:7], v[34:35]
	v_pk_fma_f32 v[36:37], v[132:133], v[8:9], v[36:37]
	v_pk_fma_f32 v[30:31], v[150:151], v[14:15], v[30:31]
	v_pk_fma_f32 v[32:33], v[152:153], v[16:17], v[32:33]
	v_pk_fma_f32 v[34:35], v[138:139], v[2:3], v[34:35]
	v_pk_fma_f32 v[36:37], v[140:141], v[4:5], v[36:37]
	v_pk_mul_f32 v[42:43], v[30:31], s[6:7] op_sel_hi:[1,0]
	v_pk_mul_f32 v[44:45], v[32:33], s[6:7] op_sel_hi:[1,0]
	v_exp_f32_e32 v42, v42
	v_exp_f32_e32 v43, v43
	v_exp_f32_e32 v44, v44
	v_exp_f32_e32 v45, v45
	v_pk_add_f32 v[42:43], v[42:43], 1.0 op_sel_hi:[1,0]
	v_pk_add_f32 v[44:45], v[44:45], 1.0 op_sel_hi:[1,0]
	v_rcp_f32_e32 v46, v42
	v_rcp_f32_e32 v47, v43
	v_rcp_f32_e32 v48, v44
	v_rcp_f32_e32 v49, v45
	v_pk_mul_f32 v[46:47], v[30:31], v[46:47]
	v_pk_mul_f32 v[48:49], v[32:33], v[48:49]
	v_pk_mul_f32 v[34:35], v[34:35], v[46:47]
	v_pk_mul_f32 v[36:37], v[36:37], v[48:49]
	v_cvt_pk_bf16_f32 v66, v34, v35
	v_cvt_pk_bf16_f32 v67, v36, v37
	global_store_dwordx2 v[58:59], v[66:67], off
	v_lshl_add_u64 v[58:59], v[58:59], 0, v[56:57]
	s_waitcnt lgkmcnt(0)
	v_lshlrev_b32_e32 v6, 16, v26
	v_and_b32_e32 v7, 0xffff0000, v26
	v_lshlrev_b32_e32 v8, 16, v27
	v_and_b32_e32 v9, 0xffff0000, v27
	v_lshlrev_b32_e32 v18, 16, v28
	v_and_b32_e32 v19, 0xffff0000, v28
	v_lshlrev_b32_e32 v20, 16, v29
	v_and_b32_e32 v21, 0xffff0000, v29
	v_add_u32_e32 v63, 0x210, v63
	ds_read2_b64 v[26:29], v63 offset1:32
	v_pk_fma_f32 v[30:31], v[146:147], v[14:15], v[158:159]
	v_pk_fma_f32 v[32:33], v[148:149], v[16:17], v[160:161]
	v_pk_fma_f32 v[34:35], v[134:135], v[2:3], v[154:155]
	v_pk_fma_f32 v[36:37], v[136:137], v[4:5], v[156:157]
	v_pk_fma_f32 v[30:31], v[142:143], v[22:23], v[30:31]
	v_pk_fma_f32 v[32:33], v[144:145], v[24:25], v[32:33]
	v_pk_fma_f32 v[34:35], v[130:131], v[10:11], v[34:35]
	v_pk_fma_f32 v[36:37], v[132:133], v[12:13], v[36:37]
	v_pk_fma_f32 v[30:31], v[150:151], v[18:19], v[30:31]
	v_pk_fma_f32 v[32:33], v[152:153], v[20:21], v[32:33]
	v_pk_fma_f32 v[34:35], v[138:139], v[6:7], v[34:35]
	v_pk_fma_f32 v[36:37], v[140:141], v[8:9], v[36:37]
	v_pk_mul_f32 v[42:43], v[30:31], s[6:7] op_sel_hi:[1,0]
	v_pk_mul_f32 v[44:45], v[32:33], s[6:7] op_sel_hi:[1,0]
	v_exp_f32_e32 v42, v42
	v_exp_f32_e32 v43, v43
	v_exp_f32_e32 v44, v44
	v_exp_f32_e32 v45, v45
	v_pk_add_f32 v[42:43], v[42:43], 1.0 op_sel_hi:[1,0]
	v_pk_add_f32 v[44:45], v[44:45], 1.0 op_sel_hi:[1,0]
	v_rcp_f32_e32 v46, v42
	v_rcp_f32_e32 v47, v43
	v_rcp_f32_e32 v48, v44
	v_rcp_f32_e32 v49, v45
	v_pk_mul_f32 v[46:47], v[30:31], v[46:47]
	v_pk_mul_f32 v[48:49], v[32:33], v[48:49]
	v_pk_mul_f32 v[34:35], v[34:35], v[46:47]
	v_pk_mul_f32 v[36:37], v[36:37], v[48:49]
	v_cvt_pk_bf16_f32 v66, v34, v35
	v_cvt_pk_bf16_f32 v67, v36, v37
	s_and_saveexec_b64 s[4:5], vcc
	global_store_dwordx2 v[58:59], v[66:67], off
	s_or_b64 exec, exec, s[4:5]
	v_lshl_add_u64 v[58:59], v[58:59], 0, v[56:57]
	s_waitcnt lgkmcnt(0)
	v_lshlrev_b32_e32 v10, 16, v26
	v_and_b32_e32 v11, 0xffff0000, v26
	v_lshlrev_b32_e32 v12, 16, v27
	v_and_b32_e32 v13, 0xffff0000, v27
	v_lshlrev_b32_e32 v22, 16, v28
	v_and_b32_e32 v23, 0xffff0000, v28
	v_lshlrev_b32_e32 v24, 16, v29
	v_and_b32_e32 v25, 0xffff0000, v29
	v_pk_fma_f32 v[30:31], v[146:147], v[18:19], v[158:159]
	v_pk_fma_f32 v[32:33], v[148:149], v[20:21], v[160:161]
	v_pk_fma_f32 v[34:35], v[134:135], v[6:7], v[154:155]
	v_pk_fma_f32 v[36:37], v[136:137], v[8:9], v[156:157]
	v_pk_fma_f32 v[30:31], v[142:143], v[14:15], v[30:31]
	v_pk_fma_f32 v[32:33], v[144:145], v[16:17], v[32:33]
	v_pk_fma_f32 v[34:35], v[130:131], v[2:3], v[34:35]
	v_pk_fma_f32 v[36:37], v[132:133], v[4:5], v[36:37]
	v_pk_fma_f32 v[30:31], v[150:151], v[22:23], v[30:31]
	v_pk_fma_f32 v[32:33], v[152:153], v[24:25], v[32:33]
	v_pk_fma_f32 v[34:35], v[138:139], v[10:11], v[34:35]
	v_pk_fma_f32 v[36:37], v[140:141], v[12:13], v[36:37]
	v_pk_mul_f32 v[42:43], v[30:31], s[6:7] op_sel_hi:[1,0]
	v_pk_mul_f32 v[44:45], v[32:33], s[6:7] op_sel_hi:[1,0]
	v_exp_f32_e32 v42, v42
	v_exp_f32_e32 v43, v43
	v_exp_f32_e32 v44, v44
	v_exp_f32_e32 v45, v45
	v_pk_add_f32 v[42:43], v[42:43], 1.0 op_sel_hi:[1,0]
	v_pk_add_f32 v[44:45], v[44:45], 1.0 op_sel_hi:[1,0]
	v_rcp_f32_e32 v46, v42
	v_rcp_f32_e32 v47, v43
	v_rcp_f32_e32 v48, v44
	v_rcp_f32_e32 v49, v45
	v_pk_mul_f32 v[46:47], v[30:31], v[46:47]
	v_pk_mul_f32 v[48:49], v[32:33], v[48:49]
	v_pk_mul_f32 v[34:35], v[34:35], v[46:47]
	v_pk_mul_f32 v[36:37], v[36:37], v[48:49]
	v_cvt_pk_bf16_f32 v66, v34, v35
	v_cvt_pk_bf16_f32 v67, v36, v37
	s_and_saveexec_b64 s[4:5], vcc
	global_store_dwordx2 v[58:59], v[66:67], off
	s_or_b64 exec, exec, s[4:5]
	v_lshl_add_u64 v[58:59], v[58:59], 0, v[56:57]
	s_branch .Lconv_done
